# v33 + mixer phases: workgroups on the critical path (M1 all, M2 LRU-final units) leave without the final work-queue poll
# speedup vs baseline: 1.0047x; 1.0047x over previous
; __global__ void __launch_bounds__(NTHREADS, 2) fwd(Args a) {
;     ...
;             int u = bx;
;             while (u < total) {
;                 if (sp == 1) { if (u < NTILE) lru_unit<0>(a, lds, l, u); else conv_unit(a, lds, l, u - NTILE); }
;                 else {
;                     if (u < nT) lru_unit<1>(a, lds, l, u);
;                     else if (u < 2 * nT - 120) conv_unit(a, lds, l, 120 + (u - nT));
;                     else if (u < 3 * nT - 120) sgu_unit(a, lds, l, u - (2 * nT - 120));
;                     else pool_unit(a, lds, l, u - (3 * nT - 120));
;                 }
;                 if (threadIdx.x == 0) qw[0] = G + (int)__hip_atomic_fetch_add(qcnt, 1u, __ATOMIC_RELAXED, __HIP_MEMORY_SCOPE_AGENT);
;                 __syncthreads();
;                 u = qw[0];
;                 __syncthreads();
;             }
.LBB0_776:
	s_waitcnt lgkmcnt(0)
	s_and_b64 vcc, exec, s[76:77]
	s_cbranch_vccnz .Lq_sp2
	s_cmp_ge_i32 s95, s54
	s_cbranch_scc1 .LBB0_785
	s_branch .Lq_poll
.Lq_sp2:
	s_cmp_lt_i32 s82, s52
	s_cbranch_scc0 .Lq_poll
	s_cmp_gt_i32 s95, s52
	s_cbranch_scc1 .LBB0_785
